# P7 EpiUp: the eight rs1 row loads issued together (was one dependent round trip each); four-slot quarter loop; otherwise as the previous version
# speedup vs baseline: 1.0135x; 1.0031x over previous
.Lq5_entry:
	v_mov_b32_e32 v4, 0
	v_mov_b32_e32 v5, 0
	v_mov_b32_e32 v6, 0
	v_mov_b32_e32 v7, 0
	v_mov_b32_e32 v8, 0
	v_mov_b32_e32 v9, 0
	v_mov_b32_e32 v10, 0
	v_mov_b32_e32 v11, 0
	v_mov_b32_e32 v12, 0
	v_mov_b32_e32 v13, 0
	v_mov_b32_e32 v14, 0
	v_mov_b32_e32 v15, 0
	v_mov_b32_e32 v16, 0
	v_mov_b32_e32 v17, 0
	v_mov_b32_e32 v18, 0
	v_mov_b32_e32 v19, 0
	v_mov_b32_e32 v20, 0
	v_mov_b32_e32 v21, 0
	v_mov_b32_e32 v22, 0
	v_mov_b32_e32 v23, 0
	v_mov_b32_e32 v24, 0
	v_mov_b32_e32 v25, 0
	v_mov_b32_e32 v26, 0
	v_mov_b32_e32 v27, 0
	v_mov_b32_e32 v28, 0
	v_mov_b32_e32 v29, 0
	v_mov_b32_e32 v30, 0
	v_mov_b32_e32 v31, 0
	v_mov_b32_e32 v32, 0
	v_mov_b32_e32 v33, 0
	v_mov_b32_e32 v34, 0
	v_mov_b32_e32 v35, 0
	v_mov_b32_e32 v36, 0
	v_mov_b32_e32 v37, 0
	v_mov_b32_e32 v38, 0
	v_mov_b32_e32 v39, 0
	v_mov_b32_e32 v40, 0
	v_mov_b32_e32 v41, 0
	v_mov_b32_e32 v42, 0
	v_mov_b32_e32 v43, 0
	v_mov_b32_e32 v44, 0
	v_mov_b32_e32 v45, 0
	v_mov_b32_e32 v46, 0
	v_mov_b32_e32 v47, 0
	v_mov_b32_e32 v48, 0
	v_mov_b32_e32 v49, 0
	v_mov_b32_e32 v50, 0
	v_mov_b32_e32 v51, 0
	v_cmp_ne_u32_e64 s[2:3], 1, v217
	s_andn2_b64 vcc, exec, s[26:27]
	s_add_u32 s56, s34, 0xfff80080
	s_addc_u32 s57, s35, -1
	s_cmp_eq_u32 s77, 12
	s_cselect_b32 s59, s39, s57
	s_cselect_b32 s58, s38, s56
	s_cselect_b32 s57, s47, s41
	s_cselect_b32 s56, s46, s18
	s_mov_b32 m0, s51
	v_lshl_add_u64 v[2:3], s[56:57], 0, v[198:199]
	s_add_u32 s78, s56, 0x80000
	global_load_lds_dwordx4 v[2:3], off
	v_lshl_add_u64 v[204:205], s[56:57], 0, v[196:197]
	s_mov_b32 m0, s60
	s_addc_u32 s79, s57, 0
	global_load_lds_dwordx4 v[204:205], off
	v_lshl_add_u64 v[206:207], s[78:79], 0, v[198:199]
	s_mov_b32 m0, s66
	v_lshl_add_u64 v[208:209], s[58:59], 0, v[196:197]
	v_lshl_add_u64 v[206:207], s[78:79], 0, v[196:197]
	s_mov_b32 m0, s67
	s_and_b64 vcc, exec, s[2:3]
	v_lshl_add_u64 v[206:207], s[58:59], 0, v[198:199]
	s_mov_b32 m0, s62
	s_nop 0
	global_load_lds_dwordx4 v[206:207], off
	s_mov_b32 m0, s63
	s_nop 0
	global_load_lds_dwordx4 v[208:209], off
	s_and_b64 vcc, exec, s[2:3]
	s_mov_b32 m0, s70
	v_lshl_add_u64 v[2:3], v[2:3], 0, s[16:17]
	s_add_u32 s56, s56, 0x80080
	global_load_lds_dwordx4 v[2:3], off
	v_lshl_add_u64 v[2:3], v[204:205], 0, s[16:17]
	s_mov_b32 m0, s71
	s_addc_u32 s57, s57, 0
	global_load_lds_dwordx4 v[2:3], off
	v_lshl_add_u64 v[2:3], s[56:57], 0, v[198:199]
	s_add_i32 m0, s48, 0x20000
	s_and_b64 vcc, exec, s[2:3]
	v_lshl_add_u64 v[2:3], s[56:57], 0, v[196:197]
	s_add_i32 m0, s48, 0x22000
	s_nop 0
	v_lshl_add_u64 v[2:3], v[206:207], 0, s[16:17]
	s_add_i32 m0, s48, 0xc000
	s_nop 0
	global_load_lds_dwordx4 v[2:3], off
	v_lshl_add_u64 v[2:3], v[208:209], 0, s[16:17]
	s_add_i32 m0, s48, 0xe000
	s_nop 0
	global_load_lds_dwordx4 v[2:3], off
	s_add_u32 s34, s34, 0x100
	s_addc_u32 s35, s35, 0
	s_add_u32 s18, s18, 0x100
	s_addc_u32 s41, s41, 0
	s_branch .Lq5_top
	s_nop 0
	s_nop 0
	s_nop 0
	s_nop 0
	s_nop 0
	s_nop 0
	s_nop 0
	s_nop 0
	s_nop 0
	s_nop 0
	s_nop 0
	s_nop 0
	s_nop 0
	s_nop 0

.LBB0_1281:
	s_cmp_lt_i32 s79, 1
	s_cselect_b64 s[34:35], -1, 0
	s_add_u32 s38, s38, 0x80080
	s_addc_u32 s39, s39, 0
	v_mov_b32_e32 v2, v0
	v_mov_b32_e32 v3, v0
	s_add_u32 s16, s4, 0x100
	v_mov_b32_e32 v1, v0
	v_mov_b32_e32 v112, 0
	v_mov_b64_e32 v[6:7], v[2:3]
	v_mov_b64_e32 v[10:11], v[2:3]
	v_mov_b64_e32 v[22:23], v[2:3]
	v_mov_b64_e32 v[26:27], v[2:3]
	v_mov_b64_e32 v[38:39], v[2:3]
	v_mov_b64_e32 v[42:43], v[2:3]
	v_mov_b64_e32 v[54:55], v[2:3]
	v_mov_b64_e32 v[58:59], v[2:3]
	v_mov_b64_e32 v[14:15], v[2:3]
	v_mov_b64_e32 v[18:19], v[2:3]
	v_mov_b64_e32 v[30:31], v[2:3]
	v_mov_b64_e32 v[34:35], v[2:3]
	v_mov_b64_e32 v[46:47], v[2:3]
	v_mov_b64_e32 v[50:51], v[2:3]
	v_mov_b64_e32 v[62:63], v[2:3]
	v_mov_b64_e32 v[66:67], v[2:3]
	v_mov_b64_e32 v[90:91], v[2:3]
	v_mov_b64_e32 v[106:107], v[2:3]
	v_mov_b64_e32 v[110:111], v[2:3]
	v_mov_b64_e32 v[118:119], v[2:3]
	v_mov_b64_e32 v[126:127], v[2:3]
	v_mov_b64_e32 v[130:131], v[2:3]
	v_mov_b64_e32 v[142:143], v[2:3]
	v_mov_b64_e32 v[146:147], v[2:3]
	s_addc_u32 s27, s5, 0
	s_mov_b32 s84, -2
	v_cndmask_b32_e64 v251, 0, 1, s[34:35]
	v_mov_b64_e32 v[4:5], v[0:1]
	v_mov_b64_e32 v[8:9], v[0:1]
	v_mov_b64_e32 v[20:21], v[0:1]
	v_mov_b64_e32 v[24:25], v[0:1]
	v_mov_b64_e32 v[36:37], v[0:1]
	v_mov_b64_e32 v[40:41], v[0:1]
	v_mov_b64_e32 v[52:53], v[0:1]
	v_mov_b64_e32 v[56:57], v[0:1]
	v_mov_b64_e32 v[12:13], v[0:1]
	v_mov_b64_e32 v[16:17], v[0:1]
	v_mov_b64_e32 v[28:29], v[0:1]
	v_mov_b64_e32 v[32:33], v[0:1]
	v_mov_b64_e32 v[44:45], v[0:1]
	v_mov_b64_e32 v[48:49], v[0:1]
	v_mov_b64_e32 v[60:61], v[0:1]
	v_mov_b64_e32 v[64:65], v[0:1]
	v_mov_b64_e32 v[88:89], v[0:1]
	v_mov_b64_e32 v[104:105], v[0:1]
	v_mov_b64_e32 v[108:109], v[0:1]
	v_mov_b64_e32 v[116:117], v[0:1]
	v_mov_b64_e32 v[124:125], v[0:1]
	v_mov_b64_e32 v[128:129], v[0:1]
	v_mov_b64_e32 v[140:141], v[0:1]
	v_mov_b64_e32 v[144:145], v[0:1]
	v_mov_b32_e32 v113, v112
	v_mov_b32_e32 v114, v112
	v_mov_b32_e32 v115, v112
	v_mov_b32_e32 v120, v112
	v_mov_b32_e32 v121, v112
	v_mov_b32_e32 v122, v112
	v_mov_b32_e32 v123, v112
	v_mov_b32_e32 v132, v112
	v_mov_b32_e32 v133, v112
	v_mov_b32_e32 v134, v112
	v_mov_b32_e32 v135, v112
	v_mov_b32_e32 v136, v112
	v_mov_b32_e32 v137, v112
	v_mov_b32_e32 v138, v112
	v_mov_b32_e32 v139, v112
	v_mov_b32_e32 v148, v112
	v_mov_b32_e32 v149, v112
	v_mov_b32_e32 v150, v112
	v_mov_b32_e32 v151, v112
	v_mov_b32_e32 v152, v112
	v_mov_b32_e32 v153, v112
	v_mov_b32_e32 v154, v112
	v_mov_b32_e32 v155, v112
	v_mov_b32_e32 v156, v112
	v_mov_b32_e32 v157, v112
	v_mov_b32_e32 v158, v112
	v_mov_b32_e32 v159, v112
	v_mov_b32_e32 v160, v112
	v_mov_b32_e32 v161, v112
	v_mov_b32_e32 v162, v112
	v_mov_b32_e32 v163, v112
	s_branch .LBB0_1283
	s_nop 0
	s_nop 0
	s_nop 0
	s_nop 0
	s_nop 0
	s_nop 0
	s_nop 0
	s_nop 0
	s_nop 0
	s_nop 0
	s_nop 0

.Lq6_entry:
	v_mov_b32_e32 v4, 0
	v_mov_b32_e32 v5, 0
	v_mov_b32_e32 v6, 0
	v_mov_b32_e32 v7, 0
	v_mov_b32_e32 v8, 0
	v_mov_b32_e32 v9, 0
	v_mov_b32_e32 v10, 0
	v_mov_b32_e32 v11, 0
	v_mov_b32_e32 v12, 0
	v_mov_b32_e32 v13, 0
	v_mov_b32_e32 v14, 0
	v_mov_b32_e32 v15, 0
	v_mov_b32_e32 v16, 0
	v_mov_b32_e32 v17, 0
	v_mov_b32_e32 v18, 0
	v_mov_b32_e32 v19, 0
	v_mov_b32_e32 v20, 0
	v_mov_b32_e32 v21, 0
	v_mov_b32_e32 v22, 0
	v_mov_b32_e32 v23, 0
	v_mov_b32_e32 v24, 0
	v_mov_b32_e32 v25, 0
	v_mov_b32_e32 v26, 0
	v_mov_b32_e32 v27, 0
	v_mov_b32_e32 v28, 0
	v_mov_b32_e32 v29, 0
	v_mov_b32_e32 v30, 0
	v_mov_b32_e32 v31, 0
	v_mov_b32_e32 v32, 0
	v_mov_b32_e32 v33, 0
	v_mov_b32_e32 v34, 0
	v_mov_b32_e32 v35, 0
	v_mov_b32_e32 v36, 0
	v_mov_b32_e32 v37, 0
	v_mov_b32_e32 v38, 0
	v_mov_b32_e32 v39, 0
	v_mov_b32_e32 v40, 0
	v_mov_b32_e32 v41, 0
	v_mov_b32_e32 v42, 0
	v_mov_b32_e32 v43, 0
	v_mov_b32_e32 v44, 0
	v_mov_b32_e32 v45, 0
	v_mov_b32_e32 v46, 0
	v_mov_b32_e32 v47, 0
	v_mov_b32_e32 v48, 0
	v_mov_b32_e32 v49, 0
	v_mov_b32_e32 v50, 0
	v_mov_b32_e32 v51, 0
	v_cmp_ne_u32_e64 s[4:5], 1, v251
	s_andn2_b64 vcc, exec, s[34:35]
	s_add_u32 s40, s38, 0xfff80080
	s_addc_u32 s41, s39, -1
	s_cmp_eq_u32 s84, 28
	s_cselect_b32 s47, s29, s41
	s_cselect_b32 s46, s28, s40
	s_cselect_b32 s41, s37, s27
	s_cselect_b32 s40, s36, s16
	s_mov_b32 m0, s49
	v_lshl_add_u64 v[2:3], s[40:41], 0, v[230:231]
	s_add_u32 s86, s40, 0x80000
	global_load_lds_dwordx4 v[2:3], off
	v_lshl_add_u64 v[236:237], s[40:41], 0, v[228:229]
	s_mov_b32 m0, s50
	s_addc_u32 s87, s41, 0
	global_load_lds_dwordx4 v[236:237], off
	v_lshl_add_u64 v[54:55], s[86:87], 0, v[230:231]
	s_mov_b32 m0, s61
	v_lshl_add_u64 v[238:239], s[46:47], 0, v[230:231]
	v_lshl_add_u64 v[54:55], s[86:87], 0, v[228:229]
	s_mov_b32 m0, s62
	v_lshl_add_u64 v[240:241], s[46:47], 0, v[228:229]
	s_mov_b32 m0, s56
	s_and_b64 vcc, exec, s[4:5]
	global_load_lds_dwordx4 v[238:239], off
	s_mov_b32 m0, s57
	s_nop 0
	global_load_lds_dwordx4 v[240:241], off
	s_and_b64 vcc, exec, s[4:5]
	s_mov_b32 m0, s65
	v_lshl_add_u64 v[2:3], v[2:3], 0, s[14:15]
	s_add_u32 s40, s40, 0x80080
	global_load_lds_dwordx4 v[2:3], off
	v_lshl_add_u64 v[2:3], v[236:237], 0, s[14:15]
	s_mov_b32 m0, s66
	s_addc_u32 s41, s41, 0
	global_load_lds_dwordx4 v[2:3], off
	v_lshl_add_u64 v[2:3], s[40:41], 0, v[230:231]
	s_add_i32 m0, s44, 0x20000
	s_and_b64 vcc, exec, s[4:5]
	v_lshl_add_u64 v[2:3], s[40:41], 0, v[228:229]
	s_add_i32 m0, s44, 0x22000
	s_nop 0
	v_lshl_add_u64 v[2:3], v[238:239], 0, s[14:15]
	s_add_i32 m0, s44, 0xc000
	s_nop 0
	global_load_lds_dwordx4 v[2:3], off
	v_lshl_add_u64 v[2:3], v[240:241], 0, s[14:15]
	s_add_i32 m0, s44, 0xe000
	s_nop 0
	global_load_lds_dwordx4 v[2:3], off
	s_add_u32 s38, s38, 0x100
	s_addc_u32 s39, s39, 0
	s_add_u32 s16, s16, 0x100
	s_addc_u32 s27, s27, 0
	s_branch .Lq6_top
	s_nop 0

.LBB0_1390:
	s_mul_i32 s9, s6, s9
	s_sub_i32 s9, s13, s9
	s_sext_i32_i16 s9, s9
	s_add_i32 s7, s7, s9
	s_lshl_b32 s20, s7, 8
	s_ashr_i32 s21, s20, 31
	s_lshl_b64 s[20:21], s[20:21], 12
	s_add_u32 s86, s80, s20
	v_readlane_b32 s9, v253, 50
	s_addc_u32 s87, s9, s21
	s_and_b64 s[18:19], s[18:19], exec
	s_cselect_b32 s9, s87, s15
	s_cselect_b32 s13, s86, s14
	s_add_u32 s14, s14, 0x80080
	s_addc_u32 s15, s15, 0
	s_add_u32 s20, s16, 0x100
	v_mov_b32_e32 v84, 0
	s_addc_u32 s21, s17, 0
	s_mov_b32 s22, -2
	v_mov_b32_e32 v85, v84
	v_mov_b32_e32 v86, v84
	v_mov_b32_e32 v87, v84
	v_mov_b32_e32 v56, v84
	v_mov_b32_e32 v57, v84
	v_mov_b32_e32 v58, v84
	v_mov_b32_e32 v59, v84
	v_mov_b32_e32 v128, v84
	v_mov_b32_e32 v129, v84
	v_mov_b32_e32 v130, v84
	v_mov_b32_e32 v131, v84
	v_mov_b32_e32 v80, v84
	v_mov_b32_e32 v81, v84
	v_mov_b32_e32 v82, v84
	v_mov_b32_e32 v83, v84
	v_mov_b32_e32 v132, v84
	v_mov_b32_e32 v133, v84
	v_mov_b32_e32 v134, v84
	v_mov_b32_e32 v135, v84
	v_mov_b32_e32 v60, v84
	v_mov_b32_e32 v61, v84
	v_mov_b32_e32 v62, v84
	v_mov_b32_e32 v63, v84
	v_mov_b32_e32 v124, v84
	v_mov_b32_e32 v125, v84
	v_mov_b32_e32 v126, v84
	v_mov_b32_e32 v127, v84
	v_mov_b32_e32 v52, v84
	v_mov_b32_e32 v53, v84
	v_mov_b32_e32 v54, v84
	v_mov_b32_e32 v55, v84
	v_mov_b32_e32 v88, v84
	v_mov_b32_e32 v89, v84
	v_mov_b32_e32 v90, v84
	v_mov_b32_e32 v91, v84
	v_mov_b32_e32 v16, v84
	v_mov_b32_e32 v17, v84
	v_mov_b32_e32 v18, v84
	v_mov_b32_e32 v19, v84
	v_mov_b32_e32 v120, v84
	v_mov_b32_e32 v121, v84
	v_mov_b32_e32 v122, v84
	v_mov_b32_e32 v123, v84
	v_mov_b32_e32 v48, v84
	v_mov_b32_e32 v49, v84
	v_mov_b32_e32 v50, v84
	v_mov_b32_e32 v51, v84
	v_mov_b32_e32 v92, v84
	v_mov_b32_e32 v93, v84
	v_mov_b32_e32 v94, v84
	v_mov_b32_e32 v95, v84
	v_mov_b32_e32 v20, v84
	v_mov_b32_e32 v21, v84
	v_mov_b32_e32 v22, v84
	v_mov_b32_e32 v23, v84
	v_mov_b32_e32 v0, v84
	v_mov_b32_e32 v1, v84
	v_mov_b32_e32 v2, v84
	v_mov_b32_e32 v3, v84
	v_mov_b32_e32 v64, v84
	v_mov_b32_e32 v65, v84
	v_mov_b32_e32 v66, v84
	v_mov_b32_e32 v67, v84
	v_mov_b32_e32 v8, v84
	v_mov_b32_e32 v9, v84
	v_mov_b32_e32 v10, v84
	v_mov_b32_e32 v11, v84
	v_mov_b32_e32 v72, v84
	v_mov_b32_e32 v73, v84
	v_mov_b32_e32 v74, v84
	v_mov_b32_e32 v75, v84
	v_mov_b32_e32 v4, v84
	v_mov_b32_e32 v5, v84
	v_mov_b32_e32 v6, v84
	v_mov_b32_e32 v7, v84
	v_mov_b32_e32 v68, v84
	v_mov_b32_e32 v69, v84
	v_mov_b32_e32 v70, v84
	v_mov_b32_e32 v71, v84
	v_mov_b32_e32 v12, v84
	v_mov_b32_e32 v13, v84
	v_mov_b32_e32 v14, v84
	v_mov_b32_e32 v15, v84
	v_mov_b32_e32 v76, v84
	v_mov_b32_e32 v77, v84
	v_mov_b32_e32 v78, v84
	v_mov_b32_e32 v79, v84
	v_mov_b32_e32 v32, v84
	v_mov_b32_e32 v33, v84
	v_mov_b32_e32 v34, v84
	v_mov_b32_e32 v35, v84
	v_mov_b32_e32 v104, v84
	v_mov_b32_e32 v105, v84
	v_mov_b32_e32 v106, v84
	v_mov_b32_e32 v107, v84
	v_mov_b32_e32 v40, v84
	v_mov_b32_e32 v41, v84
	v_mov_b32_e32 v42, v84
	v_mov_b32_e32 v43, v84
	v_mov_b32_e32 v112, v84
	v_mov_b32_e32 v113, v84
	v_mov_b32_e32 v114, v84
	v_mov_b32_e32 v115, v84
	v_mov_b32_e32 v136, v84
	v_mov_b32_e32 v137, v84
	v_mov_b32_e32 v138, v84
	v_mov_b32_e32 v139, v84
	v_mov_b32_e32 v36, v84
	v_mov_b32_e32 v37, v84
	v_mov_b32_e32 v38, v84
	v_mov_b32_e32 v39, v84
	v_mov_b32_e32 v108, v84
	v_mov_b32_e32 v109, v84
	v_mov_b32_e32 v110, v84
	v_mov_b32_e32 v111, v84
	v_mov_b32_e32 v44, v84
	v_mov_b32_e32 v45, v84
	v_mov_b32_e32 v46, v84
	v_mov_b32_e32 v47, v84
	v_mov_b32_e32 v116, v84
	v_mov_b32_e32 v117, v84
	v_mov_b32_e32 v118, v84
	v_mov_b32_e32 v119, v84
	v_mov_b32_e32 v140, v84
	v_mov_b32_e32 v141, v84
	v_mov_b32_e32 v142, v84
	v_mov_b32_e32 v143, v84
	s_nop 0
	s_nop 0
	s_nop 0
	s_nop 0
	s_nop 0
	s_nop 0
	s_nop 0
	s_nop 0
	s_nop 0
	s_nop 0
	s_nop 0
	s_nop 0

.LBB0_1398:
	s_sext_i32_i16 s12, s12
	v_lshl_or_b32 v196, s12, 7, v223
	s_lshl_b64 s[12:13], s[14:15], 2
	v_readlane_b32 s14, v253, 55
	s_add_u32 s12, s14, s12
	v_readlane_b32 s14, v253, 56
	s_addc_u32 s13, s14, s13
	v_ashrrev_i32_e32 v197, 31, v196
	v_lshl_add_u64 v[28:29], v[196:197], 2, s[12:13]
	global_load_dwordx4 v[96:99], v[28:29], off
	global_load_dwordx4 v[24:27], v[28:29], off offset:64
	v_add_co_u32_e32 v28, vcc, 0x5000, v28
	v_add_u32_e32 v202, s43, v221
	s_nop 0
	v_addc_co_u32_e32 v29, vcc, 0, v29, vcc
	global_load_dwordx4 v[100:103], v[28:29], off offset:2048
	s_nop 0
	global_load_dwordx4 v[28:31], v[28:29], off offset:2112
	v_lshlrev_b32_e32 v154, 2, v202
	global_load_dword v172, v154, s[46:47]
	global_load_dword v173, v154, s[46:47] offset:64
	global_load_dword v174, v154, s[46:47] offset:128
	global_load_dword v175, v154, s[46:47] offset:192
	global_load_dword v176, v154, s[46:47] offset:512
	global_load_dword v177, v154, s[46:47] offset:576
	global_load_dword v178, v154, s[46:47] offset:640
	global_load_dword v179, v154, s[46:47] offset:704
	v_cmp_le_i32_e32 vcc, s9, v202
	v_cmp_gt_i32_e64 s[12:13], s42, v202
	s_and_b64 vcc, vcc, s[12:13]
	v_mov_b32_e32 v206, 0
	v_mov_b32_e32 v144, 0
	s_and_saveexec_b64 s[14:15], vcc
	s_cbranch_execz .LBB0_1400
	v_ashrrev_i32_e32 v203, 31, v202
	v_lshl_add_u64 v[144:145], v[202:203], 2, s[46:47]
	s_waitcnt vmcnt(0)
	v_mov_b32_e32 v144, v172
	v_fmamk_f32 v144, v144, 0x3a000000, v237
	v_mul_f32_e32 v145, 0x4b800000, v144
	v_cmp_gt_f32_e64 s[12:13], s4, v144
	s_nop 1
	v_cndmask_b32_e64 v144, v144, v145, s[12:13]
	v_rsq_f32_e32 v144, v144
	s_nop 0
	v_mul_f32_e32 v145, 0x45800000, v144
	v_cndmask_b32_e64 v144, v144, v145, s[12:13]
.LBB0_1400:
	s_or_b64 exec, exec, s[14:15]
	v_or_b32_e32 v146, 16, v202
	v_cmp_le_i32_e64 s[12:13], s9, v146
	v_cmp_gt_i32_e64 s[14:15], s42, v146
	s_and_b64 s[18:19], s[12:13], s[14:15]
	s_and_saveexec_b64 s[14:15], s[18:19]
	s_cbranch_execz .LBB0_1402
	v_ashrrev_i32_e32 v147, 31, v146
	v_lshl_add_u64 v[146:147], v[146:147], 2, s[46:47]
	s_waitcnt vmcnt(0)
	v_mov_b32_e32 v145, v173
	v_fmamk_f32 v145, v145, 0x3a000000, v237
	v_mul_f32_e32 v146, 0x4b800000, v145
	v_cmp_gt_f32_e64 s[12:13], s4, v145
	s_nop 1
	v_cndmask_b32_e64 v145, v145, v146, s[12:13]
	v_rsq_f32_e32 v145, v145
	s_nop 0
	v_mul_f32_e32 v146, 0x45800000, v145
	v_cndmask_b32_e64 v206, v145, v146, s[12:13]
.LBB0_1402:
	s_or_b64 exec, exec, s[14:15]
	v_or_b32_e32 v148, 32, v202
	v_cmp_le_i32_e64 s[12:13], s9, v148
	v_cmp_gt_i32_e64 s[14:15], s42, v148
	s_and_b64 s[16:17], s[12:13], s[14:15]
	v_mov_b32_e32 v146, 0
	v_mov_b32_e32 v204, 0
	s_and_saveexec_b64 s[14:15], s[16:17]
	s_cbranch_execz .LBB0_1404
	v_ashrrev_i32_e32 v149, 31, v148
	v_lshl_add_u64 v[148:149], v[148:149], 2, s[46:47]
	s_waitcnt vmcnt(0)
	v_mov_b32_e32 v145, v174
	v_fmamk_f32 v145, v145, 0x3a000000, v237
	v_mul_f32_e32 v147, 0x4b800000, v145
	v_cmp_gt_f32_e64 s[12:13], s4, v145
	s_nop 1
	v_cndmask_b32_e64 v145, v145, v147, s[12:13]
	v_rsq_f32_e32 v145, v145
	s_nop 0
	v_mul_f32_e32 v147, 0x45800000, v145
	v_cndmask_b32_e64 v204, v145, v147, s[12:13]
.LBB0_1404:
	s_or_b64 exec, exec, s[14:15]
	v_or_b32_e32 v148, 48, v202
	v_cmp_le_i32_e64 s[12:13], s9, v148
	v_cmp_gt_i32_e64 s[14:15], s42, v148
	s_and_b64 s[20:21], s[12:13], s[14:15]
	s_and_saveexec_b64 s[14:15], s[20:21]
	s_cbranch_execz .LBB0_1406
	v_ashrrev_i32_e32 v149, 31, v148
	v_lshl_add_u64 v[146:147], v[148:149], 2, s[46:47]
	s_waitcnt vmcnt(0)
	v_mov_b32_e32 v145, v175
	v_fmamk_f32 v145, v145, 0x3a000000, v237
	v_mul_f32_e32 v146, 0x4b800000, v145
	v_cmp_gt_f32_e64 s[12:13], s4, v145
	s_nop 1
	v_cndmask_b32_e64 v145, v145, v146, s[12:13]
	v_rsq_f32_e32 v145, v145
	s_nop 0
	v_mul_f32_e32 v146, 0x45800000, v145
	v_cndmask_b32_e64 v146, v145, v146, s[12:13]
.LBB0_1406:
	s_or_b64 exec, exec, s[14:15]
	v_add_u32_e32 v150, 0x80, v202
	v_cmp_le_i32_e64 s[12:13], s9, v150
	v_cmp_gt_i32_e64 s[14:15], s42, v150
	s_and_b64 s[22:23], s[12:13], s[14:15]
	v_mov_b32_e32 v200, 0
	v_mov_b32_e32 v148, 0
	s_and_saveexec_b64 s[14:15], s[22:23]
	s_cbranch_execz .LBB0_1408
	v_ashrrev_i32_e32 v151, 31, v150
	v_lshl_add_u64 v[148:149], v[150:151], 2, s[46:47]
	s_waitcnt vmcnt(0)
	v_mov_b32_e32 v145, v176
	v_fmamk_f32 v145, v145, 0x3a000000, v237
	v_mul_f32_e32 v147, 0x4b800000, v145
	v_cmp_gt_f32_e64 s[12:13], s4, v145
	s_nop 1
	v_cndmask_b32_e64 v145, v145, v147, s[12:13]
	v_rsq_f32_e32 v145, v145
	s_nop 0
	v_mul_f32_e32 v147, 0x45800000, v145
	v_cndmask_b32_e64 v148, v145, v147, s[12:13]
.LBB0_1408:
	s_or_b64 exec, exec, s[14:15]
	v_add_u32_e32 v150, 0x90, v202
	v_cmp_le_i32_e64 s[12:13], s9, v150
	v_cmp_gt_i32_e64 s[14:15], s42, v150
	s_and_b64 s[14:15], s[12:13], s[14:15]
	s_and_saveexec_b64 s[24:25], s[14:15]
	s_cbranch_execz .LBB0_1410
	v_ashrrev_i32_e32 v151, 31, v150
	v_lshl_add_u64 v[150:151], v[150:151], 2, s[46:47]
	s_waitcnt vmcnt(0)
	v_mov_b32_e32 v145, v177
	v_fmamk_f32 v145, v145, 0x3a000000, v237
	v_mul_f32_e32 v147, 0x4b800000, v145
	v_cmp_gt_f32_e64 s[12:13], s4, v145
	s_nop 1
	v_cndmask_b32_e64 v145, v145, v147, s[12:13]
	v_rsq_f32_e32 v145, v145
	s_nop 0
	v_mul_f32_e32 v147, 0x45800000, v145
	v_cndmask_b32_e64 v200, v145, v147, s[12:13]
.LBB0_1410:
	s_or_b64 exec, exec, s[24:25]
	v_add_u32_e32 v152, 0xa0, v202
	v_cmp_le_i32_e64 s[12:13], s9, v152
	v_cmp_gt_i32_e64 s[24:25], s42, v152
	s_and_b64 s[12:13], s[12:13], s[24:25]
	v_mov_b32_e32 v150, 0
	v_mov_b32_e32 v198, 0
	s_and_saveexec_b64 s[28:29], s[12:13]
	s_cbranch_execz .LBB0_1412
	v_ashrrev_i32_e32 v153, 31, v152
	v_lshl_add_u64 v[152:153], v[152:153], 2, s[46:47]
	s_waitcnt vmcnt(0)
	v_mov_b32_e32 v145, v178
	v_fmamk_f32 v145, v145, 0x3a000000, v237
	v_mul_f32_e32 v147, 0x4b800000, v145
	v_cmp_gt_f32_e64 s[24:25], s4, v145
	s_nop 1
	v_cndmask_b32_e64 v145, v145, v147, s[24:25]
	v_rsq_f32_e32 v145, v145
	s_nop 0
	v_mul_f32_e32 v147, 0x45800000, v145
	v_cndmask_b32_e64 v198, v145, v147, s[24:25]
.LBB0_1412:
	s_or_b64 exec, exec, s[28:29]
	v_add_u32_e32 v152, 0xb0, v202
	v_cmp_le_i32_e64 s[24:25], s9, v152
	v_cmp_gt_i32_e64 s[28:29], s42, v152
	s_and_b64 s[24:25], s[24:25], s[28:29]
	s_and_saveexec_b64 s[34:35], s[24:25]
	s_cbranch_execz .LBB0_1414
	v_ashrrev_i32_e32 v153, 31, v152
	v_lshl_add_u64 v[150:151], v[152:153], 2, s[46:47]
	s_waitcnt vmcnt(0)
	v_mov_b32_e32 v145, v179
	v_fmamk_f32 v145, v145, 0x3a000000, v237
	v_mul_f32_e32 v147, 0x4b800000, v145
	v_cmp_gt_f32_e64 s[28:29], s4, v145
	s_nop 1
	v_cndmask_b32_e64 v145, v145, v147, s[28:29]
	v_rsq_f32_e32 v145, v145
	s_nop 0
	v_mul_f32_e32 v147, 0x45800000, v145
	v_cndmask_b32_e64 v150, v145, v147, s[28:29]

.LBB0_1625:
	s_add_i32 s30, s16, -2
	s_add_u32 s26, s26, 0x160080
	s_addc_u32 s27, s27, 0
	s_add_u32 s31, s34, 0x100
	v_mov_b32_e32 v0, 0
	s_addc_u32 s33, s35, 0
	s_mov_b32 s34, 0
	v_mov_b32_e32 v1, v0
	v_mov_b32_e32 v2, v0
	v_mov_b32_e32 v3, v0
	v_mov_b32_e32 v4, v0
	v_mov_b32_e32 v5, v0
	v_mov_b32_e32 v6, v0
	v_mov_b32_e32 v7, v0
	v_mov_b32_e32 v12, v0
	v_mov_b32_e32 v13, v0
	v_mov_b32_e32 v14, v0
	v_mov_b32_e32 v15, v0
	v_mov_b32_e32 v20, v0
	v_mov_b32_e32 v21, v0
	v_mov_b32_e32 v22, v0
	v_mov_b32_e32 v23, v0
	v_mov_b32_e32 v28, v0
	v_mov_b32_e32 v29, v0
	v_mov_b32_e32 v30, v0
	v_mov_b32_e32 v31, v0
	v_mov_b32_e32 v36, v0
	v_mov_b32_e32 v37, v0
	v_mov_b32_e32 v38, v0
	v_mov_b32_e32 v39, v0
	v_mov_b32_e32 v44, v0
	v_mov_b32_e32 v45, v0
	v_mov_b32_e32 v46, v0
	v_mov_b32_e32 v47, v0
	v_mov_b32_e32 v52, v0
	v_mov_b32_e32 v53, v0
	v_mov_b32_e32 v54, v0
	v_mov_b32_e32 v55, v0
	v_mov_b32_e32 v8, v0
	v_mov_b32_e32 v9, v0
	v_mov_b32_e32 v10, v0
	v_mov_b32_e32 v11, v0
	v_mov_b32_e32 v16, v0
	v_mov_b32_e32 v17, v0
	v_mov_b32_e32 v18, v0
	v_mov_b32_e32 v19, v0
	v_mov_b32_e32 v24, v0
	v_mov_b32_e32 v25, v0
	v_mov_b32_e32 v26, v0
	v_mov_b32_e32 v27, v0
	v_mov_b32_e32 v32, v0
	v_mov_b32_e32 v33, v0
	v_mov_b32_e32 v34, v0
	v_mov_b32_e32 v35, v0
	v_mov_b32_e32 v40, v0
	v_mov_b32_e32 v41, v0
	v_mov_b32_e32 v42, v0
	v_mov_b32_e32 v43, v0
	v_mov_b32_e32 v48, v0
	v_mov_b32_e32 v49, v0
	v_mov_b32_e32 v50, v0
	v_mov_b32_e32 v51, v0
	v_mov_b32_e32 v56, v0
	v_mov_b32_e32 v57, v0
	v_mov_b32_e32 v58, v0
	v_mov_b32_e32 v59, v0
	v_mov_b32_e32 v60, v0
	v_mov_b32_e32 v61, v0
	v_mov_b32_e32 v62, v0
	v_mov_b32_e32 v63, v0
	v_mov_b32_e32 v64, v0
	v_mov_b32_e32 v65, v0
	v_mov_b32_e32 v66, v0
	v_mov_b32_e32 v67, v0
	v_mov_b32_e32 v68, v0
	v_mov_b32_e32 v69, v0
	v_mov_b32_e32 v70, v0
	v_mov_b32_e32 v71, v0
	v_mov_b32_e32 v76, v0
	v_mov_b32_e32 v77, v0
	v_mov_b32_e32 v78, v0
	v_mov_b32_e32 v79, v0
	v_mov_b32_e32 v84, v0
	v_mov_b32_e32 v85, v0
	v_mov_b32_e32 v86, v0
	v_mov_b32_e32 v87, v0
	v_mov_b32_e32 v92, v0
	v_mov_b32_e32 v93, v0
	v_mov_b32_e32 v94, v0
	v_mov_b32_e32 v95, v0
	v_mov_b32_e32 v100, v0
	v_mov_b32_e32 v101, v0
	v_mov_b32_e32 v102, v0
	v_mov_b32_e32 v103, v0
	v_mov_b32_e32 v108, v0
	v_mov_b32_e32 v109, v0
	v_mov_b32_e32 v110, v0
	v_mov_b32_e32 v111, v0
	v_mov_b32_e32 v116, v0
	v_mov_b32_e32 v117, v0
	v_mov_b32_e32 v118, v0
	v_mov_b32_e32 v119, v0
	v_mov_b32_e32 v72, v0
	v_mov_b32_e32 v73, v0
	v_mov_b32_e32 v74, v0
	v_mov_b32_e32 v75, v0
	v_mov_b32_e32 v80, v0
	v_mov_b32_e32 v81, v0
	v_mov_b32_e32 v82, v0
	v_mov_b32_e32 v83, v0
	v_mov_b32_e32 v88, v0
	v_mov_b32_e32 v89, v0
	v_mov_b32_e32 v90, v0
	v_mov_b32_e32 v91, v0
	v_mov_b32_e32 v96, v0
	v_mov_b32_e32 v97, v0
	v_mov_b32_e32 v98, v0
	v_mov_b32_e32 v99, v0
	v_mov_b32_e32 v104, v0
	v_mov_b32_e32 v105, v0
	v_mov_b32_e32 v106, v0
	v_mov_b32_e32 v107, v0
	v_mov_b32_e32 v112, v0
	v_mov_b32_e32 v113, v0
	v_mov_b32_e32 v114, v0
	v_mov_b32_e32 v115, v0
	v_mov_b32_e32 v120, v0
	v_mov_b32_e32 v121, v0
	v_mov_b32_e32 v122, v0
	v_mov_b32_e32 v123, v0
	v_mov_b32_e32 v124, v0
	v_mov_b32_e32 v125, v0
	v_mov_b32_e32 v126, v0
	v_mov_b32_e32 v127, v0
	s_nop 0
	s_nop 0
	s_nop 0
	s_nop 0
	s_nop 0
	s_nop 0
	s_nop 0
	s_nop 0
